# P0 row loop: x rows prefetched two iterations ahead (two load buffers, loop unrolled by two)
# baseline (speedup 1.0000x reference)
.LBB0_82:
	s_or_b64 exec, exec, s[0:1]
	v_readlane_b32 s22, v245, 7
	v_readlane_b32 s23, v245, 8
	s_cmpk_lt_i32 s24, 0x4000
	s_waitcnt lgkmcnt(0)
	s_barrier
	s_cbranch_scc0 .LBB0_95
	s_ashr_i32 s25, s24, 31
	s_lshl_b64 s[0:1], s[24:25], 12
	s_add_u32 s0, s76, s0
	v_lshlrev_b32_e32 v38, 4, v37
	s_addc_u32 s1, s77, s1
	global_load_dwordx4 v[0:3], v38, s[78:79] offset:3072
	global_load_dwordx4 v[4:7], v38, s[78:79] offset:2048
	global_load_dwordx4 v[8:11], v38, s[78:79] offset:1024
	global_load_dwordx4 v[12:15], v38, s[78:79]
	global_load_dwordx4 v[16:19], v38, s[0:1] nt
	global_load_dwordx4 v[20:23], v38, s[0:1] offset:1024 nt
	global_load_dwordx4 v[24:27], v38, s[0:1] offset:2048 nt
	global_load_dwordx4 v[28:31], v38, s[0:1] offset:3072 nt
	v_and_b32_e32 v40, 16, v33
	v_cmp_eq_u32_e64 s[4:5], 0, v40
	v_and_b32_e32 v40, 8, v33
	v_and_b32_e32 v35, 64, v36
	v_cmp_eq_u32_e64 s[6:7], 0, v40
	v_and_b32_e32 v40, 4, v33
	v_add_u32_e32 v35, 64, v35
	v_cmp_eq_u32_e64 s[8:9], 0, v40
	v_xor_b32_e32 v40, 32, v36
	v_cmp_lt_i32_e32 vcc, v40, v35
	s_ashr_i32 s21, s15, 31
	s_ashr_i32 s22, s3, 31
	v_cndmask_b32_e32 v40, v36, v40, vcc
	v_lshlrev_b32_e32 v62, 2, v40
	v_xor_b32_e32 v40, 16, v36
	v_cmp_lt_i32_e32 vcc, v40, v35
	s_add_u32 s20, s15, s3
	s_addc_u32 s21, s21, s22
	v_cndmask_b32_e32 v40, v36, v40, vcc
	v_lshlrev_b32_e32 v63, 2, v40
	v_xor_b32_e32 v40, 8, v36
	v_cmp_lt_i32_e32 vcc, v40, v35
	s_lshl_b64 s[22:23], s[20:21], 5
	s_add_u32 s22, s92, s22
	v_cndmask_b32_e32 v40, v36, v40, vcc
	v_lshlrev_b32_e32 v64, 2, v40
	v_xor_b32_e32 v40, 4, v36
	v_cmp_lt_i32_e32 vcc, v40, v35
	v_cmp_gt_u32_e64 s[12:13], 32, v37
	s_addc_u32 s23, s93, s23
	v_cndmask_b32_e32 v40, v36, v40, vcc
	s_ashr_i32 s29, s28, 31
	v_lshlrev_b32_e32 v65, 2, v40
	v_xor_b32_e32 v40, 2, v36
	v_cmp_eq_u32_e64 s[10:11], 0, v34
	v_cndmask_b32_e64 v34, 8, 0, s[12:13]
	v_lshrrev_b32_e32 v33, 2, v33
	s_lshl_b64 s[26:27], s[28:29], 5
	s_lshl_b64 s[20:21], s[20:21], 11
	v_mov_b32_e32 v39, 0
	v_cmp_lt_i32_e32 vcc, v40, v35
	v_and_or_b32 v33, v33, 7, v34
	s_add_u32 s20, s74, s20
	v_cndmask_b32_e32 v40, v36, v40, vcc
	v_lshlrev_b32_e32 v34, 2, v33
	v_mov_b32_e32 v33, v39
	s_addc_u32 s21, s75, s21
	v_lshlrev_b32_e32 v66, 2, v40
	v_xor_b32_e32 v40, 1, v36
	v_lshl_add_u64 v[54:55], s[20:21], 0, v[32:33]
	s_add_i32 s20, s24, s28
	v_cmp_lt_i32_e32 vcc, v40, v35
	s_ashr_i32 s21, s20, 31
	s_lshl_b64 s[30:31], s[28:29], 11
	v_cndmask_b32_e32 v35, v36, v40, vcc
	s_lshl_b64 s[20:21], s[20:21], 12
	v_lshlrev_b32_e32 v67, 2, v35
	v_mov_b32_e32 v35, v39
	s_add_u32 s20, s76, s20
	v_lshl_add_u64 v[48:49], s[86:87], 0, v[34:35]
	v_lshl_add_u64 v[50:51], s[84:85], 0, v[34:35]
	v_lshl_add_u64 v[34:35], s[22:23], 0, v[34:35]
	s_mov_b64 s[22:23], 0x100000
	s_addc_u32 s21, s77, s21
	v_add_u32_e32 v61, 0, v38
	v_cmp_lt_u32_e64 s[0:1], 31, v37
	v_lshl_add_u64 v[52:53], v[34:35], 0, s[22:23]
	v_lshl_add_u64 v[56:57], s[20:21], 0, v[38:39]
	s_lshl_b64 s[34:35], s[28:29], 12
	v_mov_b32_e32 v68, 0x358637bd
	s_mov_b32 s3, 0xbfb8aa3b
	s_mov_b32 s15, 0x42ce8ed0
	s_mov_b32 s20, 0xc2b17218
	s_mov_b32 s21, 0x7f800000
	s_mov_b32 s22, 0x41a00000
	s_mov_b32 s23, 0x3fb8aa3b
	s_mov_b32 s25, 0xc2ce8ed0
	s_mov_b32 s29, 0x42b17218
	s_mov_b32 s42, 0x3f2aaaab
	v_mov_b32_e32 v69, 0x3ecc95a3
	s_mov_b32 s43, 0x3f317218
	s_mov_b32 s44, 0x33800000
	v_mov_b32_e32 v70, 0x7f800000
	v_mov_b32_e32 v58, 0x3f317218
	s_andn2_b64 s[38:39], s[10:11], s[0:1]
	s_mov_b64 s[40:41], exec
	s_and_b64 exec, exec, s[38:39]
	global_load_dword v136, v[48:49], off
	global_load_dword v137, v[50:51], off
	s_mov_b64 exec, s[40:41]
	s_add_i32 s32, s24, s28
	s_cmpk_gt_i32 s32, 0x3fff
	s_cbranch_scc1 .Lp0_nor1
	global_load_dwordx4 v[140:143], v[56:57], off nt
	global_load_dwordx4 v[144:147], v[56:57], off offset:1024 nt
	global_load_dwordx4 v[148:151], v[56:57], off offset:2048 nt
	global_load_dwordx4 v[152:155], v[56:57], off offset:3072 nt
.Lp0_nor1:
	v_lshl_add_u64 v[56:57], v[56:57], 0, s[34:35]
	s_waitcnt vmcnt(0)
	s_branch .LBB0_86

.Lr0_86:
	s_add_i32 s24, s24, s28
	s_cmpk_gt_i32 s24, 0x3fff
	s_cselect_b64 s[36:37], -1, 0
	s_waitcnt vmcnt(16)
	v_mov_b64_e32 v[34:35], v[154:155]
	v_mov_b64_e32 v[38:39], v[150:151]
	v_mov_b64_e32 v[42:43], v[146:147]
	v_mov_b64_e32 v[46:47], v[142:143]
	v_mov_b64_e32 v[32:33], v[152:153]
	v_mov_b64_e32 v[36:37], v[148:149]
	v_mov_b64_e32 v[40:41], v[144:145]
	v_mov_b64_e32 v[44:45], v[140:141]
	s_add_i32 s32, s24, s28
	s_cmpk_gt_i32 s32, 0x3fff
	s_cbranch_scc1 .Lr0_88
	global_load_dwordx4 v[140:143], v[56:57], off nt
	global_load_dwordx4 v[144:147], v[56:57], off offset:1024 nt
	global_load_dwordx4 v[148:151], v[56:57], off offset:2048 nt
	global_load_dwordx4 v[152:155], v[56:57], off offset:3072 nt

.Lr0_91:
	s_andn2_saveexec_b64 s[40:41], s[40:41]
	s_cbranch_execz .Lr0_85
	v_mov_b32_e32 v33, v136
	v_add_f32_e32 v32, v32, v33
	v_cmp_nlt_f32_e32 vcc, s22, v32
	s_and_saveexec_b64 s[40:41], vcc
	s_cbranch_execz .Lr0_84
	v_mul_f32_e32 v33, 0x3fb8aa3b, v32
	v_rndne_f32_e32 v34, v33
	v_sub_f32_e32 v35, v33, v34
	v_fma_f32 v33, v32, s23, -v33
	v_fmac_f32_e32 v33, 0x32a5705f, v32
	v_add_f32_e32 v33, v35, v33
	v_cvt_i32_f32_e32 v34, v34
	v_exp_f32_e32 v33, v33
	v_cmp_ngt_f32_e32 vcc, s25, v32
	v_ldexp_f32 v33, v33, v34
	s_nop 0
	v_cndmask_b32_e32 v33, 0, v33, vcc
	v_cmp_nlt_f32_e32 vcc, s29, v32
	s_nop 1
	v_cndmask_b32_e32 v46, v70, v33, vcc
	v_add_f32_e32 v34, 1.0, v46
	v_add_f32_e32 v32, -1.0, v34
	v_sub_f32_e32 v33, v32, v34
	v_add_f32_e32 v33, 1.0, v33
	v_sub_f32_e32 v32, v46, v32
	v_add_f32_e32 v35, v32, v33
	v_frexp_mant_f32_e32 v36, v34
	v_cvt_f64_f32_e32 v[32:33], v34
	v_frexp_exp_i32_f64_e32 v32, v[32:33]
	v_cmp_gt_f32_e32 vcc, s42, v36
	s_nop 1
	v_subbrev_co_u32_e32 v40, vcc, 0, v32, vcc
	v_sub_u32_e32 v32, 0, v40
	v_ldexp_f32 v33, v34, v32
	v_add_f32_e32 v34, -1.0, v33
	v_add_f32_e32 v36, 1.0, v33
	v_ldexp_f32 v32, v35, v32
	v_add_f32_e32 v35, 1.0, v34
	v_add_f32_e32 v37, -1.0, v36
	v_sub_f32_e32 v35, v33, v35
	v_sub_f32_e32 v33, v33, v37
	v_add_f32_e32 v35, v32, v35
	v_add_f32_e32 v32, v32, v33
	v_add_f32_e32 v41, v36, v32
	v_rcp_f32_e32 v43, v41
	v_sub_f32_e32 v33, v36, v41
	v_add_f32_e32 v42, v32, v33
	v_add_f32_e32 v33, v34, v35
	v_mul_f32_e32 v45, v33, v43
	v_sub_f32_e32 v32, v34, v33
	v_mul_f32_e32 v34, v41, v45
	v_fma_f32 v36, v45, v41, -v34
	v_fmac_f32_e32 v36, v45, v42
	v_add_f32_e32 v44, v35, v32
	v_add_f32_e32 v32, v34, v36
	v_sub_f32_e32 v35, v33, v32
	v_pk_add_f32 v[38:39], v[32:33], v[34:35] neg_lo:[0,1] neg_hi:[0,1]
	v_mov_b32_e32 v37, v32
	v_pk_add_f32 v[32:33], v[38:39], v[36:37] neg_lo:[0,1] neg_hi:[0,1]
	v_cmp_neq_f32_e32 vcc, s21, v46
	v_add_f32_e32 v33, v44, v33
	v_add_f32_e32 v32, v32, v33
	v_add_f32_e32 v33, v35, v32
	v_mul_f32_e32 v44, v43, v33
	v_mul_f32_e32 v34, v41, v44
	v_fma_f32 v36, v44, v41, -v34
	v_fmac_f32_e32 v36, v44, v42
	v_sub_f32_e32 v35, v35, v33
	v_add_f32_e32 v41, v32, v35
	v_add_f32_e32 v32, v34, v36
	v_sub_f32_e32 v35, v33, v32
	v_pk_add_f32 v[38:39], v[32:33], v[34:35] neg_lo:[0,1] neg_hi:[0,1]
	v_mov_b32_e32 v37, v32
	v_pk_add_f32 v[32:33], v[38:39], v[36:37] neg_lo:[0,1] neg_hi:[0,1]
	s_nop 0
	v_add_f32_e32 v33, v41, v33
	v_add_f32_e32 v32, v32, v33
	v_add_f32_e32 v33, v45, v44
	v_add_f32_e32 v32, v35, v32
	v_sub_f32_e32 v34, v33, v45
	v_mul_f32_e32 v32, v43, v32
	v_sub_f32_e32 v34, v44, v34
	v_add_f32_e32 v34, v34, v32
	v_add_f32_e32 v36, v33, v34
	v_mul_f32_e32 v37, v36, v36
	v_fmamk_f32 v32, v37, 0x3e9b6dac, v69
	v_fmaak_f32 v59, v37, v32, 0x3f2aaada
	v_cvt_f32_i32_e32 v32, v40
	v_sub_f32_e32 v33, v36, v33
	v_sub_f32_e32 v33, v34, v33
	v_ldexp_f32 v38, v33, 1
	v_mul_f32_e32 v33, v36, v37
	v_ldexp_f32 v35, v36, 1
	v_pk_mul_f32 v[36:37], v[32:33], v[58:59]
	s_nop 0
	v_fma_f32 v34, v32, s43, -v36
	v_fmac_f32_e32 v34, 0xb102e308, v32
	v_pk_add_f32 v[32:33], v[36:37], v[34:35]
	s_nop 0
	v_sub_f32_e32 v35, v33, v35
	v_sub_f32_e32 v35, v37, v35
	v_add_f32_e32 v39, v38, v35
	v_mov_b32_e32 v38, v36
	v_pk_add_f32 v[36:37], v[32:33], v[36:37] neg_lo:[0,1] neg_hi:[0,1]
	v_pk_add_f32 v[40:41], v[32:33], v[38:39]
	v_mov_b32_e32 v35, v32
	v_mov_b32_e32 v37, v41
	v_pk_add_f32 v[42:43], v[34:35], v[36:37] neg_lo:[0,1] neg_hi:[0,1]
	v_pk_add_f32 v[34:35], v[34:35], v[36:37]
	v_mov_b32_e32 v38, v39
	v_pk_add_f32 v[36:37], v[34:35], v[32:33] op_sel:[1,0] op_sel_hi:[0,1] neg_lo:[0,1] neg_hi:[0,1]
	v_pk_add_f32 v[44:45], v[40:41], v[36:37] op_sel_hi:[1,0] neg_lo:[0,1] neg_hi:[0,1]
	v_mov_b32_e32 v40, v41
	v_mov_b32_e32 v41, v35
	v_pk_mov_b32 v[36:37], v[32:33], v[36:37] op_sel:[1,0]
	v_mov_b32_e32 v39, v32
	v_pk_add_f32 v[36:37], v[40:41], v[36:37] neg_lo:[0,1] neg_hi:[0,1]
	v_mov_b32_e32 v44, v42
	v_pk_add_f32 v[32:33], v[38:39], v[36:37] neg_lo:[0,1] neg_hi:[0,1]
	v_mov_b32_e32 v43, v35
	v_pk_add_f32 v[36:37], v[44:45], v[32:33]
	s_nop 0
	v_pk_add_f32 v[38:39], v[36:37], v[36:37] op_sel:[0,1] op_sel_hi:[1,0]
	s_nop 0
	v_pk_add_f32 v[34:35], v[34:35], v[38:39] op_sel:[1,0] op_sel_hi:[0,1]
	v_mov_b32_e32 v37, v34
	v_pk_add_f32 v[40:41], v[36:37], v[42:43] neg_lo:[0,1] neg_hi:[0,1]
	v_mov_b32_e32 v33, v38
	v_sub_f32_e32 v35, v36, v40
	v_pk_add_f32 v[32:33], v[32:33], v[40:41] neg_lo:[0,1] neg_hi:[0,1]
	v_sub_f32_e32 v35, v42, v35
	v_add_f32_e32 v32, v32, v35
	v_add_f32_e32 v32, v32, v33
	v_add_f32_e32 v32, v34, v32
	v_cndmask_b32_e32 v32, v70, v32, vcc
	v_cmp_lt_f32_e64 vcc, |v46|, s44
	s_nop 1
	v_cndmask_b32_e32 v32, v32, v46, vcc
	s_branch .Lr0_84
.Lr0_84:
	s_or_b64 exec, exec, s[40:41]
	v_mov_b32_e32 v33, v137
	v_mul_f32_e32 v34, 0x3fb8aa3b, v33
	v_rndne_f32_e32 v35, v34
	v_fma_f32 v36, v33, s23, -v34
	v_sub_f32_e32 v34, v34, v35
	v_fmac_f32_e32 v36, 0x32a5705f, v33
	v_add_f32_e32 v34, v34, v36
	v_cvt_i32_f32_e32 v35, v35
	v_exp_f32_e32 v34, v34
	v_cmp_ngt_f32_e32 vcc, s25, v33
	v_ldexp_f32 v34, v34, v35
	s_nop 0
	v_cndmask_b32_e32 v34, 0, v34, vcc
	v_cmp_nlt_f32_e32 vcc, s29, v33
	s_nop 1
	v_cndmask_b32_e32 v33, v70, v34, vcc
	v_mul_f32_e64 v32, v32, -v33
	global_store_dword v[52:53], v32, off

.LBB0_86:
	s_add_i32 s24, s24, s28
	s_cmpk_gt_i32 s24, 0x3fff
	s_cselect_b64 s[36:37], -1, 0
	s_waitcnt vmcnt(16)
	v_mov_b64_e32 v[34:35], v[30:31]
	v_mov_b64_e32 v[38:39], v[26:27]
	v_mov_b64_e32 v[42:43], v[22:23]
	v_mov_b64_e32 v[46:47], v[18:19]
	v_mov_b64_e32 v[32:33], v[28:29]
	v_mov_b64_e32 v[36:37], v[24:25]
	v_mov_b64_e32 v[40:41], v[20:21]
	v_mov_b64_e32 v[44:45], v[16:17]
	s_add_i32 s32, s24, s28
	s_cmpk_gt_i32 s32, 0x3fff
	s_cbranch_scc1 .LBB0_88
	global_load_dwordx4 v[16:19], v[56:57], off nt
	global_load_dwordx4 v[20:23], v[56:57], off offset:1024 nt
	global_load_dwordx4 v[24:27], v[56:57], off offset:2048 nt
	global_load_dwordx4 v[28:31], v[56:57], off offset:3072 nt
